# attention: unit epilogue stores widened (cvt pairs + v_permlane32_swap -> 4 dwordx4 stores per lane instead of 8 dwordx2); prologue K1/V0 tile loads issued before the K0 wait in the fixed-reference de
# speedup vs baseline: 1.0130x; 1.0012x over previous
.LBB0_405:
	v_div_scale_f32 v4, s[0:1], v0, v0, 1.0
	v_rcp_f32_e32 v5, v4
	v_div_scale_f32 v6, vcc, 1.0, v0, 1.0
	s_add_i32 s26, s26, s51
	v_fma_f32 v7, -v4, v5, 1.0
	v_fmac_f32_e32 v5, v7, v5
	v_mul_f32_e32 v7, v6, v5
	v_fma_f32 v8, -v4, v7, v6
	v_fmac_f32_e32 v7, v8, v5
	v_fma_f32 v4, -v4, v7, v6
	v_div_fmas_f32 v4, v4, v5, v7
	v_div_fixup_f32 v4, v4, v0, 1.0
	v_lshlrev_b32_e32 v0, 4, v226
	v_lshl_add_u64 v[2:3], v[2:3], 0, v[0:1]
	v_pk_mul_f32 v[16:17], v[16:17], v[4:5] op_sel_hi:[1,0]
	v_pk_mul_f32 v[18:19], v[18:19], v[4:5] op_sel_hi:[1,0]
	v_pk_mul_f32 v[20:21], v[20:21], v[4:5] op_sel_hi:[1,0]
	v_pk_mul_f32 v[22:23], v[22:23], v[4:5] op_sel_hi:[1,0]
	v_cvt_pk_bf16_f32 v48, v16, v17
	v_cvt_pk_bf16_f32 v49, v18, v19
	v_cvt_pk_bf16_f32 v50, v20, v21
	v_cvt_pk_bf16_f32 v51, v22, v23
	s_nop 1
	v_permlane32_swap_b32_e32 v48, v50
	v_permlane32_swap_b32_e32 v49, v51
	global_store_dwordx4 v[2:3], v[48:51], off
	v_pk_mul_f32 v[24:25], v[24:25], v[4:5] op_sel_hi:[1,0]
	v_pk_mul_f32 v[26:27], v[26:27], v[4:5] op_sel_hi:[1,0]
	v_pk_mul_f32 v[28:29], v[28:29], v[4:5] op_sel_hi:[1,0]
	v_pk_mul_f32 v[30:31], v[30:31], v[4:5] op_sel_hi:[1,0]
	v_cvt_pk_bf16_f32 v52, v24, v25
	v_cvt_pk_bf16_f32 v53, v26, v27
	v_cvt_pk_bf16_f32 v54, v28, v29
	v_cvt_pk_bf16_f32 v55, v30, v31
	s_nop 1
	v_permlane32_swap_b32_e32 v52, v54
	v_permlane32_swap_b32_e32 v53, v55
	global_store_dwordx4 v[2:3], v[52:55], off offset:32
	v_pk_mul_f32 v[32:33], v[32:33], v[4:5] op_sel_hi:[1,0]
	v_pk_mul_f32 v[34:35], v[34:35], v[4:5] op_sel_hi:[1,0]
	v_pk_mul_f32 v[36:37], v[36:37], v[4:5] op_sel_hi:[1,0]
	v_pk_mul_f32 v[38:39], v[38:39], v[4:5] op_sel_hi:[1,0]
	v_cvt_pk_bf16_f32 v56, v32, v33
	v_cvt_pk_bf16_f32 v57, v34, v35
	v_cvt_pk_bf16_f32 v58, v36, v37
	v_cvt_pk_bf16_f32 v59, v38, v39
	s_nop 1
	v_permlane32_swap_b32_e32 v56, v58
	v_permlane32_swap_b32_e32 v57, v59
	global_store_dwordx4 v[2:3], v[56:59], off offset:64
	v_pk_mul_f32 v[40:41], v[40:41], v[4:5] op_sel_hi:[1,0]
	v_pk_mul_f32 v[42:43], v[42:43], v[4:5] op_sel_hi:[1,0]
	v_pk_mul_f32 v[44:45], v[44:45], v[4:5] op_sel_hi:[1,0]
	v_pk_mul_f32 v[46:47], v[46:47], v[4:5] op_sel_hi:[1,0]
	v_cvt_pk_bf16_f32 v60, v40, v41
	v_cvt_pk_bf16_f32 v61, v42, v43
	v_cvt_pk_bf16_f32 v62, v44, v45
	v_cvt_pk_bf16_f32 v63, v46, v47
	s_nop 1
	v_permlane32_swap_b32_e32 v60, v62
	v_permlane32_swap_b32_e32 v61, v63
	global_store_dwordx4 v[2:3], v[60:63], off offset:96
	s_cmp_lt_i32 s26, s24
	s_cbranch_scc0 .LBB0_518

.LBB0_427:
	v_readlane_b32 s2, v254, 7
	s_lshl_b32 s1, s1, 8
	s_add_i32 s6, s0, s2
	s_and_b32 s7, s1, 0x700
	s_lshl_b32 s0, s0, 11
	v_readlane_b32 s1, v253, 40
	s_add_i32 s0, s0, s1
	s_or_b32 s4, s7, s0
	s_add_i32 s0, s8, s25
	v_readlane_b32 s76, v253, 4
	s_ashr_i32 s1, s0, 31
	v_readlane_b32 s80, v253, 8
	v_readlane_b32 s81, v253, 9
	s_ashr_i32 s2, s8, 2
	s_min_u32 s18, s7, 0x680
	s_lshl_b64 s[0:1], s[0:1], 2
	s_mov_b64 s[12:13], s[80:81]
	v_mov_b32_e32 v0, 0x80
	s_add_u32 s0, s12, s0
	v_sub_u32_e64 v0, s7, v0 clamp
	s_addc_u32 s1, s13, s1
	v_readfirstlane_b32 s28, v0
	global_load_dword v0, v1, s[0:1]
	s_mul_i32 s0, s6, 20
	s_ashr_i32 s1, s0, 31
	s_lshl_b64 s[0:1], s[0:1], 2
	s_add_u32 s5, s54, s0
	s_addc_u32 s10, s58, s1
	s_ashr_i32 s9, s8, 31
	s_lshl_b64 s[0:1], s[8:9], 2
	s_add_u32 s0, s5, s0
	s_addc_u32 s1, s10, s1
	s_ashr_i32 s3, s2, 31
	v_readlane_b32 s77, v253, 5
	v_readlane_b32 s80, v255, 3
	v_readlane_b32 s76, v255, 5
	v_readlane_b32 s81, v255, 4
	v_readlane_b32 s77, v255, 6
	v_readlane_b32 s78, v253, 6
	v_readlane_b32 s79, v253, 7
	v_readlane_b32 s82, v253, 10
	v_readlane_b32 s83, v253, 11
	s_waitcnt vmcnt(0)
	v_mul_f32_e32 v227, 0x3fb8aa3b, v0
	global_load_dword v0, v1, s[0:1] sc1
	s_lshl_b64 s[0:1], s[2:3], 2
	s_add_u32 s0, s5, s0
	s_addc_u32 s1, s10, s1
	s_ashr_i32 s5, s4, 31
	s_lshl_b64 s[4:5], s[4:5], 11
	s_waitcnt vmcnt(0)
	v_readfirstlane_b32 s9, v0
	global_load_dword v0, v1, s[0:1] offset:64 sc1
	s_waitcnt vmcnt(0)
	v_readfirstlane_b32 s0, v0
	s_nop 1
	v_mov_b32_e32 v0, s0
	v_mul_f32_e32 v0, s9, v0
	s_mov_b32 s0, 0xf800000
	v_cmp_gt_f32_e32 vcc, s0, v0
	v_mul_f32_e32 v2, 0x4f800000, v0
	s_nop 0
	v_cndmask_b32_e32 v0, v0, v2, vcc
	v_sqrt_f32_e32 v2, v0
	s_nop 0
	v_add_u32_e32 v3, -1, v2
	v_fma_f32 v4, -v3, v2, v0
	v_cmp_ge_f32_e64 s[0:1], 0, v4
	v_add_u32_e32 v4, 1, v2
	s_nop 0
	v_cndmask_b32_e64 v3, v2, v3, s[0:1]
	v_fma_f32 v2, -v4, v2, v0
	v_cmp_lt_f32_e64 s[0:1], 0, v2
	s_nop 1
	v_cndmask_b32_e64 v2, v3, v4, s[0:1]
	v_mul_f32_e32 v3, 0x37800000, v2
	v_cndmask_b32_e32 v2, v2, v3, vcc
	v_mov_b32_e32 v3, 0x260
	v_cmp_class_f32_e32 vcc, v0, v3
	s_mov_b32 s0, 0x42480000
	s_nop 0
	v_cndmask_b32_e32 v0, v2, v0, vcc
	v_fmamk_f32 v0, v0, 0x3f828f5c, v214
	v_max_f32_e32 v0, v0, v227
	v_cmp_ge_f32_e32 vcc, s0, v0
	s_mov_b32 s0, 0xc2700000
	v_cmp_le_f32_e64 s[0:1], s0, v227
	s_and_b64 s[0:1], vcc, s[0:1]
	s_add_u32 s3, s36, s4
	s_addc_u32 s10, s37, s5
	s_lshl_b32 s8, s8, 6
	s_ashr_i32 s9, s8, 31
	s_lshl_b64 s[8:9], s[8:9], 1
	s_add_u32 s14, s3, s8
	s_addc_u32 s15, s10, s9
	s_mul_i32 s10, s6, 0x120000
	s_mul_hi_i32 s3, s6, 0x120000
	s_add_u32 s12, s38, s10
	s_addc_u32 s3, s39, s3
	s_lshl_b32 s10, s2, 6
	s_ashr_i32 s11, s10, 31
	s_lshl_b64 s[10:11], s[10:11], 1
	s_add_u32 s12, s12, s10
	s_addc_u32 s13, s3, s11
	s_lshl_b32 s3, s6, 2
	s_add_i32 s2, s3, s2
	s_mul_hi_i32 s3, s2, 0x48000
	s_mul_i32 s2, s2, 0x48000
	s_add_u32 s16, s57, s2
	s_addc_u32 s17, s88, s3
	s_add_u32 s2, s84, s4
	s_addc_u32 s3, s85, s5
	s_add_u32 s10, s2, s8
	s_addc_u32 s11, s3, s9
	s_sub_i32 s29, s18, s28
	s_addk_i32 s29, 0x180
	s_lshr_b32 s6, s28, 6
	s_ashr_i32 s27, s29, 6
	s_mov_b64 s[2:3], -1
	s_andn2_b64 vcc, exec, s[0:1]
	s_cbranch_vccz .LBB0_481
	v_mov_b32_e32 v18, v209
	v_mov_b32_e32 v21, v1
	v_readfirstlane_b32 s0, v18
	s_ashr_i32 s0, s0, 1
	s_and_b32 s4, s0, 0xffffffe0
	s_add_i32 s35, s4, s7
	v_mov_b32_e32 v0, s0
	s_movk_i32 s0, 0xffe0
	s_cmp_gt_i32 s27, 0
	v_bfi_b32 v2, s0, v0, v18
	s_cselect_b64 s[0:1], -1, 0
	s_sub_i32 s5, 0x800, s29
	v_ashrrev_i32_e32 v3, 31, v2
	s_cmp_lt_i32 s27, 1
	v_bfe_u32 v226, v18, 5, 1
	v_lshlrev_b64 v[14:15], 11, v[2:3]
	s_cselect_b64 s[2:3], -1, 0
	v_lshl_add_u64 v[2:3], s[14:15], 0, v[14:15]
	v_lshlrev_b32_e32 v0, 4, v226
	s_and_b64 s[8:9], s[2:3], exec
	v_lshl_add_u64 v[16:17], v[2:3], 0, v[0:1]
	v_ashrrev_i32_e32 v228, 3, v18
	s_cselect_b32 s68, s5, s28
	global_load_dwordx4 v[2:5], v[16:17], off
	global_load_dwordx4 v[6:9], v[16:17], off offset:32
	global_load_dwordx4 v[10:13], v[16:17], off offset:64
	global_load_dwordx4 v[192:195], v[16:17], off offset:96
	v_add_u32_e32 v16, s68, v228
	v_ashrrev_i32_e32 v17, 31, v16
	v_and_b32_e32 v35, 7, v18
	v_lshlrev_b64 v[16:17], 9, v[16:17]
	v_lshl_add_u64 v[16:17], s[12:13], 0, v[16:17]
	v_lshlrev_b32_e32 v20, 4, v35
	v_lshl_add_u64 v[16:17], v[16:17], 0, v[20:21]
	v_and_b32_e32 v34, 31, v18
	global_load_dwordx4 v[16:19], v[16:17], off
	s_movk_i32 s5, 0x90
	v_mul_lo_u32 v22, v228, s5
	s_or_b32 s5, s6, 1
	s_sub_i32 s8, 33, s27
	s_cmp_gt_i32 s27, 1
	v_add3_u32 v229, 0, v22, v20
	s_cselect_b32 s5, s5, s8
	s_add_i32 s30, s35, 0xffffff80
	v_cmp_eq_u32_e32 vcc, 0, v226
	v_xor_b32_e32 v80, 0x80000000, v227
	v_mov_b32_e32 v232, 1.0
	v_cndmask_b32_e64 v231, 0, 1.0, vcc
	v_mul_u32_u24_e32 v230, 0x90, v34
	v_lshl_add_u32 v100, s5, 6, v228
	v_ashrrev_i32_e32 v101, 31, v100
	v_lshlrev_b64 v[100:101], 9, v[100:101]
	v_lshl_add_u64 v[100:101], s[12:13], 0, v[100:101]
	v_lshl_add_u64 v[100:101], v[100:101], 0, v[20:21]
	global_load_dwordx4 v[196:199], v[100:101], off
	v_mov_b64_e32 v[100:101], s[16:17]
	s_movk_i32 s5, 0x1200
	v_mad_i64_i32 v[32:33], s[8:9], v228, s5, v[100:101]
	v_lshl_add_u64 v[100:101], s[68:69], 1, v[32:33]
	v_lshl_add_u64 v[100:101], v[100:101], 0, v[20:21]
	global_load_dwordx4 v[200:203], v[100:101], off
	s_waitcnt vmcnt(2)
	ds_write_b128 v229, v[16:19]
	s_or_b32 s5, s28, 63
	s_cmp_ge_i32 s5, s30
	s_cselect_b64 s[8:9], -1, 0
	s_add_i32 s31, s35, 0x9f
	s_cmp_le_i32 s28, s31
	s_cselect_b64 s[18:19], -1, 0
	s_and_b64 s[8:9], s[8:9], s[18:19]
	s_or_b64 s[8:9], s[2:3], s[8:9]
	s_andn2_b64 vcc, exec, s[8:9]
	s_waitcnt lgkmcnt(0)
	s_barrier
	s_cbranch_vccnz .LBB0_435
	v_add3_u32 v48, 0, v230, v0
	ds_read_b128 v[16:19], v48
	ds_read_b128 v[20:23], v48 offset:32
	ds_read_b128 v[24:27], v48 offset:4608
	ds_read_b128 v[28:31], v48 offset:4640
	ds_read_b128 v[36:39], v48 offset:64
	ds_read_b128 v[40:43], v48 offset:96
	ds_read_b128 v[44:47], v48 offset:4672
	ds_read_b128 v[96:99], v48 offset:4704
	v_mov_b32_e32 v81, v80
	v_mov_b32_e32 v82, v80
	v_mov_b32_e32 v83, v80
	v_mov_b32_e32 v84, v80
	v_mov_b32_e32 v85, v80
	v_mov_b32_e32 v86, v80
	v_mov_b32_e32 v87, v80
	v_mov_b32_e32 v88, v80
	v_mov_b32_e32 v89, v80
	v_mov_b32_e32 v90, v80
	v_mov_b32_e32 v91, v80
	v_mov_b32_e32 v92, v80
	v_mov_b32_e32 v93, v80
	v_mov_b32_e32 v94, v80
	v_mov_b32_e32 v95, v80
	v_mov_b64_e32 v[64:65], v[80:81]
	v_mov_b64_e32 v[66:67], v[82:83]
	v_mov_b64_e32 v[68:69], v[84:85]
	v_mov_b64_e32 v[70:71], v[86:87]
	v_mov_b64_e32 v[72:73], v[88:89]
	v_mov_b64_e32 v[74:75], v[90:91]
	v_mov_b64_e32 v[76:77], v[92:93]
	v_mov_b64_e32 v[78:79], v[94:95]
	s_waitcnt lgkmcnt(7)
	v_mfma_f32_32x32x16_bf16 v[48:63], v[16:19], v[2:5], v[80:95]
	s_andn2_b64 vcc, exec, s[0:1]
	s_waitcnt lgkmcnt(5)
	v_mfma_f32_32x32x16_bf16 v[64:79], v[24:27], v[2:5], v[64:79]
	v_mfma_f32_32x32x16_bf16 v[48:63], v[20:23], v[6:9], v[48:63]
	s_waitcnt lgkmcnt(4)
	v_mfma_f32_32x32x16_bf16 v[64:79], v[28:31], v[6:9], v[64:79]
	s_waitcnt lgkmcnt(3)
	v_mfma_f32_32x32x16_bf16 v[48:63], v[36:39], v[10:13], v[48:63]
	s_waitcnt lgkmcnt(1)
	v_mfma_f32_32x32x16_bf16 v[64:79], v[44:47], v[10:13], v[64:79]
	v_mfma_f32_32x32x16_bf16 v[48:63], v[40:43], v[192:195], v[48:63]
	s_waitcnt lgkmcnt(0)
	v_mfma_f32_32x32x16_bf16 v[64:79], v[96:99], v[192:195], v[64:79]
	s_cbranch_vccnz .LBB0_432
	s_add_i32 s0, s35, 0xffffff9f
	s_cmp_lt_i32 s28, s0
	s_cselect_b64 s[0:1], -1, 0
	s_add_i32 s2, s35, 0x41
	s_cmp_gt_i32 s28, s2
	s_cselect_b64 s[2:3], -1, 0
	s_or_b64 s[0:1], s[0:1], s[2:3]
	s_andn2_b64 vcc, exec, s[0:1]
	s_cbranch_vccnz .LBB0_432
	v_or_b32_e32 v16, s35, v34
	v_lshl_or_b32 v17, v226, 2, s28
	v_sub_u32_e32 v16, v16, v17
	v_add_u32_e32 v17, 0x80, v16
	s_movk_i32 s0, 0x101
	v_cmp_gt_u32_e32 vcc, s0, v17
	v_add_u32_e32 v17, 0xffffff5f, v16
	s_movk_i32 s0, 0xfefe
	v_cndmask_b32_e32 v48, v216, v48, vcc
	v_cmp_lt_u32_e32 vcc, s0, v17
	v_add_u32_e32 v17, 0xffffff7e, v16
	s_nop 0
	v_cndmask_b32_e32 v64, v216, v64, vcc
	v_cmp_lt_u32_e32 vcc, s0, v17
	v_add_u32_e32 v17, 0xffffff5e, v16
	s_nop 0
	v_cndmask_b32_e32 v49, v216, v49, vcc
	v_cmp_lt_u32_e32 vcc, s0, v17
	v_add_u32_e32 v17, 0xffffff7d, v16
	s_nop 0
	v_cndmask_b32_e32 v65, v216, v65, vcc
	v_cmp_lt_u32_e32 vcc, s0, v17
	v_add_u32_e32 v17, 0xffffff5d, v16
	s_nop 0
	v_cndmask_b32_e32 v50, v216, v50, vcc
	v_cmp_lt_u32_e32 vcc, s0, v17
	v_add_u32_e32 v17, 0xffffff7c, v16
	s_nop 0
	v_cndmask_b32_e32 v66, v216, v66, vcc
	v_cmp_lt_u32_e32 vcc, s0, v17
	v_add_u32_e32 v17, 0xffffff5c, v16
	s_nop 0
	v_cndmask_b32_e32 v51, v216, v51, vcc
	v_cmp_lt_u32_e32 vcc, s0, v17
	v_add_u32_e32 v17, 0xffffff77, v16
	s_nop 0
	v_cndmask_b32_e32 v67, v216, v67, vcc
	v_cmp_lt_u32_e32 vcc, s0, v17
	v_add_u32_e32 v17, 0xffffff57, v16
	s_nop 0
	v_cndmask_b32_e32 v52, v216, v52, vcc
	v_cmp_lt_u32_e32 vcc, s0, v17
	v_add_u32_e32 v17, 0xffffff76, v16
	s_nop 0
	v_cndmask_b32_e32 v68, v216, v68, vcc
	v_cmp_lt_u32_e32 vcc, s0, v17
	v_add_u32_e32 v17, 0xffffff56, v16
	s_nop 0
	v_cndmask_b32_e32 v53, v216, v53, vcc
	v_cmp_lt_u32_e32 vcc, s0, v17
	v_add_u32_e32 v17, 0xffffff75, v16
	s_nop 0
	v_cndmask_b32_e32 v69, v216, v69, vcc
	v_cmp_lt_u32_e32 vcc, s0, v17
	v_add_u32_e32 v17, 0xffffff55, v16
	s_nop 0
	v_cndmask_b32_e32 v54, v216, v54, vcc
	v_cmp_lt_u32_e32 vcc, s0, v17
	v_add_u32_e32 v17, 0xffffff74, v16
	s_nop 0
	v_cndmask_b32_e32 v70, v216, v70, vcc
	v_cmp_lt_u32_e32 vcc, s0, v17
	v_add_u32_e32 v17, 0xffffff54, v16
	s_nop 0
	v_cndmask_b32_e32 v55, v216, v55, vcc
	v_cmp_lt_u32_e32 vcc, s0, v17
	v_add_u32_e32 v17, 0xffffff6f, v16
	s_nop 0
	v_cndmask_b32_e32 v71, v216, v71, vcc
	v_cmp_lt_u32_e32 vcc, s0, v17
	v_add_u32_e32 v17, 0xffffff4f, v16
	s_nop 0
	v_cndmask_b32_e32 v56, v216, v56, vcc
	v_cmp_lt_u32_e32 vcc, s0, v17
	v_add_u32_e32 v17, 0xffffff6e, v16
	s_nop 0
	v_cndmask_b32_e32 v72, v216, v72, vcc
	v_cmp_lt_u32_e32 vcc, s0, v17
	v_add_u32_e32 v17, 0xffffff4e, v16
	s_nop 0
	v_cndmask_b32_e32 v57, v216, v57, vcc
	v_cmp_lt_u32_e32 vcc, s0, v17
	v_add_u32_e32 v17, 0xffffff6d, v16
	s_nop 0
	v_cndmask_b32_e32 v73, v216, v73, vcc
	v_cmp_lt_u32_e32 vcc, s0, v17
	v_add_u32_e32 v17, 0xffffff4d, v16
	s_nop 0
	v_cndmask_b32_e32 v58, v216, v58, vcc
	v_cmp_lt_u32_e32 vcc, s0, v17
	v_add_u32_e32 v17, 0xffffff6c, v16
	s_nop 0
	v_cndmask_b32_e32 v74, v216, v74, vcc
	v_cmp_lt_u32_e32 vcc, s0, v17
	v_add_u32_e32 v17, 0xffffff4c, v16
	s_nop 0
	v_cndmask_b32_e32 v59, v216, v59, vcc
	v_cmp_lt_u32_e32 vcc, s0, v17
	v_add_u32_e32 v17, 0xffffff67, v16
	s_nop 0
	v_cndmask_b32_e32 v75, v216, v75, vcc
	v_cmp_lt_u32_e32 vcc, s0, v17
	v_add_u32_e32 v17, 0xffffff47, v16
	s_nop 0
	v_cndmask_b32_e32 v60, v216, v60, vcc
	v_cmp_lt_u32_e32 vcc, s0, v17
	v_add_u32_e32 v17, 0xffffff66, v16
	s_nop 0
	v_cndmask_b32_e32 v76, v216, v76, vcc
	v_cmp_lt_u32_e32 vcc, s0, v17
	v_add_u32_e32 v17, 0xffffff46, v16
	s_nop 0
	v_cndmask_b32_e32 v61, v216, v61, vcc
	v_cmp_lt_u32_e32 vcc, s0, v17
	v_add_u32_e32 v17, 0xffffff65, v16
	s_nop 0
	v_cndmask_b32_e32 v77, v216, v77, vcc
	v_cmp_lt_u32_e32 vcc, s0, v17
	v_add_u32_e32 v17, 0xffffff45, v16
	s_nop 0
	v_cndmask_b32_e32 v62, v216, v62, vcc
	v_cmp_lt_u32_e32 vcc, s0, v17
	v_add_u32_e32 v17, 0xffffff64, v16
	v_add_u32_e32 v16, 0xffffff44, v16
	v_cndmask_b32_e32 v78, v216, v78, vcc
	v_cmp_lt_u32_e32 vcc, s0, v17
	s_nop 1
	v_cndmask_b32_e32 v63, v216, v63, vcc
	v_cmp_lt_u32_e32 vcc, s0, v16
	s_nop 1
	v_cndmask_b32_e32 v79, v216, v79, vcc

.LBB0_523:
	v_add_f32_e32 v0, v34, v0
	v_div_scale_f32 v34, s[4:5], v0, v0, 1.0
	v_rcp_f32_e32 v35, v34
	s_lshl_b64 s[2:3], s[8:9], 11
	s_add_u32 s2, s84, s2
	s_addc_u32 s3, s85, s3
	v_fma_f32 v36, -v34, v35, 1.0
	v_fmac_f32_e32 v35, v36, v35
	v_div_scale_f32 v36, vcc, 1.0, v0, 1.0
	v_mul_f32_e32 v37, v36, v35
	v_fma_f32 v38, -v34, v37, v36
	v_fmac_f32_e32 v37, v38, v35
	v_fma_f32 v34, -v34, v37, v36
	v_div_fmas_f32 v34, v34, v35, v37
	s_add_u32 s2, s2, s10
	v_div_fixup_f32 v34, v34, v0, 1.0
	s_addc_u32 s3, s3, s11
	v_lshlrev_b64 v[36:37], 11, v[178:179]
	v_lshl_add_u64 v[36:37], s[2:3], 0, v[36:37]
	v_lshlrev_b32_e32 v0, 4, v181
	v_lshl_add_u64 v[36:37], v[36:37], 0, v[0:1]
	v_pk_mul_f32 v[2:3], v[2:3], v[34:35] op_sel_hi:[1,0]
	v_pk_mul_f32 v[4:5], v[4:5], v[34:35] op_sel_hi:[1,0]
	v_pk_mul_f32 v[6:7], v[6:7], v[34:35] op_sel_hi:[1,0]
	v_pk_mul_f32 v[8:9], v[8:9], v[34:35] op_sel_hi:[1,0]
	v_cvt_pk_bf16_f32 v38, v2, v3
	v_cvt_pk_bf16_f32 v39, v4, v5
	v_cvt_pk_bf16_f32 v40, v6, v7
	v_cvt_pk_bf16_f32 v41, v8, v9
	s_nop 1
	v_permlane32_swap_b32_e32 v38, v40
	v_permlane32_swap_b32_e32 v39, v41
	global_store_dwordx4 v[36:37], v[38:41], off
	v_pk_mul_f32 v[10:11], v[10:11], v[34:35] op_sel_hi:[1,0]
	v_pk_mul_f32 v[12:13], v[12:13], v[34:35] op_sel_hi:[1,0]
	v_pk_mul_f32 v[14:15], v[14:15], v[34:35] op_sel_hi:[1,0]
	v_pk_mul_f32 v[16:17], v[16:17], v[34:35] op_sel_hi:[1,0]
	v_cvt_pk_bf16_f32 v42, v10, v11
	v_cvt_pk_bf16_f32 v43, v12, v13
	v_cvt_pk_bf16_f32 v44, v14, v15
	v_cvt_pk_bf16_f32 v45, v16, v17
	s_nop 1
	v_permlane32_swap_b32_e32 v42, v44
	v_permlane32_swap_b32_e32 v43, v45
	global_store_dwordx4 v[36:37], v[42:45], off offset:32
	v_pk_mul_f32 v[18:19], v[18:19], v[34:35] op_sel_hi:[1,0]
	v_pk_mul_f32 v[20:21], v[20:21], v[34:35] op_sel_hi:[1,0]
	v_pk_mul_f32 v[22:23], v[22:23], v[34:35] op_sel_hi:[1,0]
	v_pk_mul_f32 v[24:25], v[24:25], v[34:35] op_sel_hi:[1,0]
	v_cvt_pk_bf16_f32 v46, v18, v19
	v_cvt_pk_bf16_f32 v47, v20, v21
	v_cvt_pk_bf16_f32 v48, v22, v23
	v_cvt_pk_bf16_f32 v49, v24, v25
	s_nop 1
	v_permlane32_swap_b32_e32 v46, v48
	v_permlane32_swap_b32_e32 v47, v49
	global_store_dwordx4 v[36:37], v[46:49], off offset:64
	v_pk_mul_f32 v[26:27], v[26:27], v[34:35] op_sel_hi:[1,0]
	v_pk_mul_f32 v[28:29], v[28:29], v[34:35] op_sel_hi:[1,0]
	v_pk_mul_f32 v[30:31], v[30:31], v[34:35] op_sel_hi:[1,0]
	v_pk_mul_f32 v[32:33], v[32:33], v[34:35] op_sel_hi:[1,0]
	v_cvt_pk_bf16_f32 v50, v26, v27
	v_cvt_pk_bf16_f32 v51, v28, v29
	v_cvt_pk_bf16_f32 v52, v30, v31
	v_cvt_pk_bf16_f32 v53, v32, v33
	s_nop 1
	v_permlane32_swap_b32_e32 v50, v52
	v_permlane32_swap_b32_e32 v51, v53
	global_store_dwordx4 v[36:37], v[50:53], off offset:96
	s_add_i32 s22, s22, s51
	s_cmp_ge_i32 s22, s6
	s_cbranch_scc1 .LBB0_577

.LBB0_531:
	v_readlane_b32 s2, v254, 7
	s_ashr_i32 s9, s8, 31
	s_add_i32 s5, s5, s2
	s_ashr_i32 s7, s4, 2
	s_lshl_b64 s[2:3], s[8:9], 10
	s_add_u32 s12, s36, s2
	s_addc_u32 s13, s37, s3
	s_lshl_b32 s2, s4, 6
	s_ashr_i32 s3, s2, 31
	s_lshl_b64 s[10:11], s[2:3], 1
	s_add_u32 s18, s12, s10
	s_addc_u32 s19, s13, s11
	s_mul_i32 s3, s5, 0x90000
	s_mul_hi_i32 s2, s5, 0x90000
	s_add_u32 s4, s38, s3
	s_addc_u32 s13, s39, s2
	s_lshl_b32 s2, s7, 6
	s_ashr_i32 s3, s2, 31
	s_lshl_b64 s[2:3], s[2:3], 1
	s_add_u32 s12, s4, s2
	s_addc_u32 s13, s13, s3
	s_lshl_b32 s2, s5, 1
	s_add_i32 s2, s2, s7
	s_mul_hi_i32 s3, s2, 0x48000
	s_mul_i32 s2, s2, 0x48000
	s_add_u32 s16, s57, s2
	s_addc_u32 s17, s88, s3
	s_andn2_b64 vcc, exec, s[0:1]
	s_mov_b64 s[2:3], -1
	s_cbranch_vccnz .LBB0_546
	v_mov_b32_e32 v4, v209
	v_mov_b32_e32 v49, v1
	v_readfirstlane_b32 s2, v4
	s_ashr_i32 s2, s2, 1
	v_bfe_u32 v181, v4, 5, 1
	v_mov_b32_e32 v0, s2
	s_movk_i32 s2, 0xffe0
	v_bfi_b32 v178, s2, v0, v4
	v_ashrrev_i32_e32 v179, 31, v178
	v_lshlrev_b64 v[2:3], 10, v[178:179]
	v_lshl_add_u64 v[2:3], s[18:19], 0, v[2:3]
	v_lshlrev_b32_e32 v0, 4, v181
	s_and_b64 s[2:3], s[14:15], exec
	v_lshl_add_u64 v[2:3], v[2:3], 0, v[0:1]
	v_ashrrev_i32_e32 v117, 3, v4
	s_cselect_b32 s7, 0, 0x800
	global_load_dwordx4 v[90:93], v[2:3], off
	global_load_dwordx4 v[86:89], v[2:3], off offset:32
	global_load_dwordx4 v[82:85], v[2:3], off offset:64
	global_load_dwordx4 v[78:81], v[2:3], off offset:96
	v_add_u32_e32 v2, s7, v117
	v_ashrrev_i32_e32 v3, 31, v2
	v_and_b32_e32 v6, 31, v4
	v_lshlrev_b64 v[2:3], 8, v[2:3]
	v_lshlrev_b32_e32 v4, 4, v4
	v_lshl_add_u64 v[2:3], s[12:13], 0, v[2:3]
	v_and_b32_e32 v48, 0x70, v4
	v_lshl_add_u64 v[2:3], v[2:3], 0, v[48:49]
	global_load_dwordx4 v[2:5], v[2:3], off
	s_movk_i32 s20, 0x90
	s_lshl_b32 s3, s23, 6
	v_mul_lo_u32 v7, v117, s20
	s_sub_i32 s2, 0x840, s3
	v_add_u32_e32 v7, 0, v7
	s_and_b64 s[4:5], s[14:15], exec
	v_add_u32_e32 v111, v7, v48
	s_cselect_b32 s2, 64, s2
	s_movk_i32 s4, 0x1200
	s_lshl_b32 s68, s7, 1
	s_or_b32 s7, s23, 4
	s_sub_i32 s3, 0x880, s3
	v_mov_b32_e32 v110, 0
	s_mov_b32 s25, 0
	v_lshl_add_u64 v[112:113], s[12:13], 0, v[48:49]
	v_add_u32_e32 v230, s2, v117
	v_ashrrev_i32_e32 v231, 31, v230
	v_lshlrev_b64 v[230:231], 8, v[230:231]
	v_lshl_add_u64 v[230:231], s[12:13], 0, v[230:231]
	v_lshl_add_u64 v[230:231], v[230:231], 0, v[48:49]
	global_load_dwordx4 v[98:101], v[230:231], off
	v_mov_b64_e32 v[230:231], s[16:17]
	v_mad_i64_i32 v[66:67], s[4:5], v117, s4, v[230:231]
	v_lshl_add_u64 v[230:231], v[66:67], 0, s[68:69]
	v_lshl_add_u64 v[230:231], v[230:231], 0, v[48:49]
	global_load_dwordx4 v[50:53], v[230:231], off
	s_waitcnt vmcnt(2)
	ds_write_b128 v111, v[2:5]
	v_mad_u32_u24 v2, v6, s20, 0
	v_add_u32_e32 v116, v2, v0
	s_waitcnt lgkmcnt(0)
	s_barrier
	ds_read_b128 v[18:21], v116 offset:4608
	ds_read_b128 v[2:5], v116
	ds_read_b128 v[22:25], v116 offset:32
	ds_read_b128 v[54:57], v116 offset:4640
	ds_read_b128 v[26:29], v116 offset:64
	ds_read_b128 v[58:61], v116 offset:4672
	ds_read_b128 v[30:33], v116 offset:96
	ds_read_b128 v[62:65], v116 offset:4704
	s_waitcnt lgkmcnt(6)
	v_mfma_f32_32x32x16_bf16 v[2:17], v[2:5], v[90:93], 0
	s_and_b64 s[4:5], s[14:15], exec
	s_cselect_b32 s3, 0x80, s3
	s_lshl_b32 s68, s2, 1
	v_lshl_add_u64 v[114:115], v[66:67], 0, v[48:49]
	s_sub_i32 s24, 0, s23
	s_waitcnt vmcnt(1)
	ds_write_b128 v111, v[98:101] offset:9216
	s_waitcnt vmcnt(0)
	ds_write_b128 v111, v[50:53] offset:18432
	s_waitcnt lgkmcnt(7)
	v_mfma_f32_32x32x16_bf16 v[2:17], v[22:25], v[86:89], v[2:17]
	s_waitcnt lgkmcnt(0)
	s_barrier
	v_mfma_f32_32x32x16_bf16 v[2:17], v[26:29], v[82:85], v[2:17]
	v_mfma_f32_32x32x16_bf16 v[2:17], v[30:33], v[78:81], v[2:17]
	v_mfma_f32_32x32x16_bf16 v[18:33], v[18:21], v[90:93], 0
	s_nop 10
	v_exp_f32_e32 v46, v2
	v_add_u32_e32 v2, s3, v117
	v_exp_f32_e32 v37, v3
	v_ashrrev_i32_e32 v3, 31, v2
	v_lshlrev_b64 v[2:3], 8, v[2:3]
	v_lshl_add_u64 v[2:3], s[12:13], 0, v[2:3]
	v_lshl_add_u64 v[2:3], v[2:3], 0, v[48:49]
	global_load_dwordx4 v[102:105], v[2:3], off
	v_lshl_add_u64 v[2:3], v[66:67], 0, s[68:69]
	v_lshl_add_u64 v[2:3], v[2:3], 0, v[48:49]
	global_load_dwordx4 v[94:97], v[2:3], off
	v_mfma_f32_32x32x16_bf16 v[18:33], v[54:57], v[86:89], v[18:33]
	v_exp_f32_e32 v44, v4
	v_exp_f32_e32 v137, v5
	v_exp_f32_e32 v42, v6
	v_exp_f32_e32 v128, v7
	v_exp_f32_e32 v40, v8
	v_exp_f32_e32 v127, v9
	v_exp_f32_e32 v134, v10
	v_mfma_f32_32x32x16_bf16 v[18:33], v[58:61], v[82:85], v[18:33]
	v_exp_f32_e32 v129, v11
	v_exp_f32_e32 v135, v12
	v_exp_f32_e32 v130, v13
	v_exp_f32_e32 v136, v14
	v_exp_f32_e32 v131, v15
	v_exp_f32_e32 v133, v16
	v_exp_f32_e32 v132, v17
	v_mfma_f32_32x32x16_bf16 v[18:33], v[62:65], v[78:81], v[18:33]
	v_mov_b32_e32 v2, 0
	v_mov_b32_e32 v3, v110
	v_mov_b32_e32 v4, v110
	v_mov_b32_e32 v5, v110
	v_mov_b32_e32 v6, v110
	v_mov_b32_e32 v7, v110
	v_mov_b32_e32 v8, v110
	s_nop 4
	v_exp_f32_e32 v0, v18
	v_exp_f32_e32 v35, v19
	v_exp_f32_e32 v38, v20
	v_exp_f32_e32 v126, v21
	v_exp_f32_e32 v34, v22
	v_exp_f32_e32 v124, v23
	v_exp_f32_e32 v36, v24
	v_exp_f32_e32 v125, v25
	v_exp_f32_e32 v39, v26
	v_exp_f32_e32 v41, v27
	v_exp_f32_e32 v118, v28
	v_exp_f32_e32 v119, v29
	v_exp_f32_e32 v120, v30
	v_exp_f32_e32 v121, v31
	v_exp_f32_e32 v122, v32
	v_exp_f32_e32 v123, v33
	v_mov_b32_e32 v9, v110
	v_mov_b32_e32 v10, v110
	v_mov_b32_e32 v11, v110
	v_mov_b32_e32 v12, v110
	v_mov_b32_e32 v13, v110
	v_mov_b32_e32 v14, v110
	v_mov_b32_e32 v15, v110
	v_mov_b32_e32 v16, v110
	v_mov_b32_e32 v17, v110
	v_mov_b32_e32 v18, 0
	v_mov_b32_e32 v19, v110
	v_mov_b32_e32 v20, v110
	v_mov_b32_e32 v21, v110
	v_mov_b32_e32 v22, v110
	v_mov_b32_e32 v23, v110
	v_mov_b32_e32 v24, v110
	v_mov_b32_e32 v25, v110
	v_mov_b32_e32 v26, v110
	v_mov_b32_e32 v27, v110
	v_mov_b32_e32 v28, v110
	v_mov_b32_e32 v29, v110
	v_mov_b32_e32 v30, v110
	v_mov_b32_e32 v31, v110
	v_mov_b32_e32 v32, v110
	v_mov_b32_e32 v33, v110
